# prologue rmsnorm row loop: norm weights loaded once, next row's loads issued before the current row's stores (no store drains inside the loop)
# baseline (speedup 1.0000x reference)
; DI unsigned cvtpk(float lo, float hi) { f32x2 v = {lo, hi}; bf16x2_t b = __builtin_convertvector(v, bf16x2_t); return __builtin_bit_cast(unsigned, b); }
; DI void rms_row_bf16(const float* xrow, const float* g, bf16* orow, int lane) {
;     f32x4 v[4]; float s = 0.f;
; #pragma unroll
;     for (int j = 0; j < 4; ++j) { v[j] = ((const f32x4*)xrow)[lane + 64 * j]; s += (v[j].x * v[j].x + v[j].y * v[j].y) + (v[j].z * v[j].z + v[j].w * v[j].w); }
;     const float r = 1.f / sqrtf(wave_sum(s) * (1.f / 1024.f) + EPS);
; #pragma unroll
;     for (int j = 0; j < 4; ++j) { const f32x4 gg = ((const f32x4*)g)[lane + 64 * j]; u32x2 o; o.x = cvtpk(v[j].x * r * gg.x, v[j].y * r * gg.y); o.y = cvtpk(v[j].z * r * gg.z, v[j].w * r * gg.w);
;         ((u32x2*)orow)[lane + 64 * j] = o; }
; }
; DI void phase0(const Ctx& c0, LAS unsigned char* lds) {
;     ...
;     for (int m = gw; m < T; m += NGW) rms_row_bf16(c.a->in[I_X] + (size_t)m * DM, c.a->in[I_GPRE], (bf16*)(c.ws + O_HB) + (size_t)m * DM, c.lane);
.LBB0_216:
	s_cmp_lt_i32 s72, 0x8000
	s_cselect_b64 s[2:3], -1, 0
	v_writelane_b32 v250, s2, 6
	s_cmpk_gt_i32 s72, 0x7fff
	s_nop 0
	v_writelane_b32 v250, s3, 7
	s_cbranch_scc1 .LBB0_219
	v_mbcnt_hi_u32_b32 v2, -1, v184
	v_and_b32_e32 v1, 64, v2
	v_add_u32_e32 v3, 64, v1
	v_xor_b32_e32 v1, 1, v2
	v_cmp_lt_i32_e32 vcc, v1, v3
	v_xor_b32_e32 v4, 2, v2
	s_ashr_i32 s73, s72, 31
	v_cndmask_b32_e32 v1, v2, v1, vcc
	v_cmp_lt_i32_e32 vcc, v4, v3
	s_waitcnt lgkmcnt(0)
	s_load_dwordx4 s[4:7], s[90:91], 0x0
	s_lshl_b64 s[2:3], s[72:73], 11
	v_cndmask_b32_e32 v4, v2, v4, vcc
	v_lshlrev_b32_e32 v8, 2, v4
	v_xor_b32_e32 v4, 4, v2
	v_cmp_lt_i32_e32 vcc, v4, v3
	v_mov_b32_e32 v7, 0
	s_add_u32 s0, s0, s2
	v_cndmask_b32_e32 v4, v2, v4, vcc
	v_lshlrev_b32_e32 v9, 2, v4
	v_xor_b32_e32 v4, 8, v2
	v_cmp_lt_i32_e32 vcc, v4, v3
	v_mov_b32_e32 v5, v7
	s_addc_u32 s1, s1, s3
	v_cndmask_b32_e32 v4, v2, v4, vcc
	v_lshlrev_b32_e32 v10, 2, v4
	v_xor_b32_e32 v4, 16, v2
	v_cmp_lt_i32_e32 vcc, v4, v3
	s_ashr_i32 s75, s74, 31
	s_lshl_b64 s[2:3], s[72:73], 12
	v_cndmask_b32_e32 v4, v2, v4, vcc
	v_lshlrev_b32_e32 v11, 2, v4
	v_xor_b32_e32 v4, 32, v2
	v_cmp_lt_i32_e32 vcc, v4, v3
	v_lshlrev_b32_e32 v6, 4, v150
	v_lshlrev_b32_e32 v1, 2, v1
	v_cndmask_b32_e32 v2, v2, v4, vcc
	v_lshlrev_b32_e32 v4, 3, v150
	v_lshl_add_u64 v[4:5], s[0:1], 0, v[4:5]
	s_mov_b64 s[0:1], 0x2400000
	v_lshl_add_u64 v[4:5], v[4:5], 0, s[0:1]
	s_lshl_b64 s[0:1], s[74:75], 11
	s_waitcnt lgkmcnt(0)
	s_add_u32 s2, s4, s2
	s_addc_u32 s3, s5, s3
	v_lshlrev_b32_e32 v12, 2, v2
	v_lshl_add_u64 v[2:3], s[6:7], 0, v[6:7]
	v_lshl_add_u64 v[6:7], s[2:3], 0, v[6:7]
	s_mov_b64 s[2:3], 0xc00
	v_lshl_add_u64 v[6:7], v[6:7], 0, s[2:3]
	s_lshl_b64 s[2:3], s[74:75], 12
	v_mov_b32_e32 v13, 0x358637bd
	s_mov_b32 s6, 0xf800000
	v_mov_b32_e32 v14, 0x260
	s_mov_b32 s7, s72
	global_load_dwordx4 v[228:231], v[2:3], off
	global_load_dwordx4 v[232:235], v[2:3], off offset:1024
	global_load_dwordx4 v[236:239], v[2:3], off offset:2048
	global_load_dwordx4 v[240:243], v[2:3], off offset:3072
	global_load_dwordx4 v[244:247], v[6:7], off offset:-3072
	global_load_dwordx4 v[188:191], v[6:7], off offset:-2048
	global_load_dwordx4 v[192:195], v[6:7], off offset:-1024
	global_load_dwordx4 v[54:57], v[6:7], off
	v_lshl_add_u64 v[6:7], v[6:7], 0, s[2:3]
	s_waitcnt vmcnt(0)
.LBB0_218:
	s_waitcnt vmcnt(4)
	v_mov_b64_e32 v[16:17], v[244:245]
	v_mov_b64_e32 v[18:19], v[246:247]
	v_mov_b64_e32 v[20:21], v[188:189]
	v_mov_b64_e32 v[22:23], v[190:191]
	v_mov_b64_e32 v[24:25], v[192:193]
	v_mov_b64_e32 v[26:27], v[194:195]
	v_mov_b64_e32 v[28:29], v[54:55]
	v_mov_b64_e32 v[30:31], v[56:57]
	s_add_i32 s7, s7, s74
	s_cmp_lt_i32 s7, 0x8000
	s_cselect_b32 s98, 1, 0
	s_cbranch_scc0 .Lp0n_skip
	global_load_dwordx4 v[244:247], v[6:7], off offset:-3072
	global_load_dwordx4 v[188:191], v[6:7], off offset:-2048
	global_load_dwordx4 v[192:195], v[6:7], off offset:-1024
	global_load_dwordx4 v[54:57], v[6:7], off
	v_lshl_add_u64 v[6:7], v[6:7], 0, s[2:3]
.Lp0n_skip:
	v_pk_mul_f32 v[36:37], v[18:19], v[18:19]
	v_pk_mul_f32 v[38:39], v[16:17], v[16:17]
	v_pk_mul_f32 v[40:41], v[22:23], v[22:23]
	v_pk_mul_f32 v[42:43], v[20:21], v[20:21]
	v_pk_mov_b32 v[48:49], v[38:39], v[36:37] op_sel:[1,0]
	v_mov_b32_e32 v39, v37
	v_pk_mov_b32 v[36:37], v[42:43], v[40:41] op_sel:[1,0]
	v_mov_b32_e32 v43, v41
	v_mul_f32_e32 v47, v29, v29
	v_mul_f32_e32 v44, v25, v25
	v_mul_f32_e32 v46, v27, v27
	v_pk_add_f32 v[38:39], v[48:49], v[38:39]
	v_pk_add_f32 v[36:37], v[36:37], v[42:43]
	v_mul_f32_e32 v15, v28, v28
	v_mul_f32_e32 v50, v30, v30
	v_mul_f32_e32 v51, v31, v31
	v_pk_fma_f32 v[40:41], v[24:25], v[24:25], v[44:45] op_sel_hi:[1,1,0]
	v_pk_fma_f32 v[44:45], v[26:27], v[26:27], v[46:47] op_sel_hi:[1,1,0]
	v_pk_add_f32 v[38:39], v[38:39], v[38:39] op_sel:[0,1] op_sel_hi:[1,0]
	v_pk_add_f32 v[36:37], v[36:37], v[36:37] op_sel:[0,1] op_sel_hi:[1,0]
	v_mov_b32_e32 v41, v50
	v_mov_b32_e32 v45, v51
	v_mov_b32_e32 v39, v15
	v_mov_b32_e32 v37, v47
	v_pk_add_f32 v[40:41], v[40:41], v[44:45]
	v_pk_add_f32 v[36:37], v[38:39], v[36:37]
	s_nop 0
	v_pk_add_f32 v[36:37], v[36:37], v[40:41]
	s_nop 0
	v_add_f32_e32 v15, v36, v37
	ds_bpermute_b32 v36, v1, v15
	s_waitcnt lgkmcnt(0)
	v_add_f32_e32 v15, v15, v36
	ds_bpermute_b32 v36, v8, v15
	s_waitcnt lgkmcnt(0)
	v_add_f32_e32 v15, v15, v36
	ds_bpermute_b32 v36, v9, v15
	s_waitcnt lgkmcnt(0)
	v_add_f32_e32 v15, v15, v36
	ds_bpermute_b32 v36, v10, v15
	s_waitcnt lgkmcnt(0)
	v_add_f32_e32 v15, v15, v36
	ds_bpermute_b32 v36, v11, v15
	s_waitcnt lgkmcnt(0)
	v_add_f32_e32 v15, v15, v36
	ds_bpermute_b32 v36, v12, v15
	s_waitcnt lgkmcnt(0)
	v_add_f32_e32 v15, v15, v36
	v_fmamk_f32 v15, v15, 0x3a800000, v13
	v_mul_f32_e32 v36, 0x4f800000, v15
	v_cmp_gt_f32_e32 vcc, s6, v15
	s_nop 1
	v_cndmask_b32_e32 v15, v15, v36, vcc
	v_sqrt_f32_e32 v36, v15
	s_nop 0
	v_add_u32_e32 v37, -1, v36
	v_add_u32_e32 v38, 1, v36
	v_fma_f32 v39, -v37, v36, v15
	v_fma_f32 v40, -v38, v36, v15
	v_cmp_ge_f32_e64 s[4:5], 0, v39
	s_nop 1
	v_cndmask_b32_e64 v36, v36, v37, s[4:5]
	v_cmp_lt_f32_e64 s[4:5], 0, v40
	s_nop 1
	v_cndmask_b32_e64 v36, v36, v38, s[4:5]
	v_mul_f32_e32 v37, 0x37800000, v36
	v_cndmask_b32_e32 v36, v36, v37, vcc
	v_cmp_class_f32_e32 vcc, v15, v14
	s_nop 1
	v_cndmask_b32_e32 v15, v36, v15, vcc
	v_div_scale_f32 v36, s[4:5], v15, v15, 1.0
	v_div_scale_f32 v37, vcc, 1.0, v15, 1.0
	v_rcp_f32_e32 v36, v15
	s_nop 0
	v_pk_mul_f32 v[16:17], v[16:17], v[36:37] op_sel_hi:[1,0]
	v_pk_mul_f32 v[18:19], v[18:19], v[36:37] op_sel_hi:[1,0]
	v_pk_mul_f32 v[16:17], v[228:229], v[16:17]
	v_pk_mul_f32 v[18:19], v[230:231], v[18:19]
	v_cvt_pk_bf16_f32 v16, v16, v17
	v_cvt_pk_bf16_f32 v17, v18, v19
	global_store_dwordx2 v[4:5], v[16:17], off
	v_pk_mul_f32 v[20:21], v[20:21], v[36:37] op_sel_hi:[1,0]
	v_pk_mul_f32 v[22:23], v[22:23], v[36:37] op_sel_hi:[1,0]
	v_pk_mul_f32 v[16:17], v[232:233], v[20:21]
	v_pk_mul_f32 v[18:19], v[234:235], v[22:23]
	v_cvt_pk_bf16_f32 v16, v16, v17
	v_cvt_pk_bf16_f32 v17, v18, v19
	global_store_dwordx2 v[4:5], v[16:17], off offset:512
	v_pk_mul_f32 v[20:21], v[24:25], v[36:37] op_sel_hi:[1,0]
	v_pk_mul_f32 v[22:23], v[26:27], v[36:37] op_sel_hi:[1,0]
	v_pk_mul_f32 v[16:17], v[236:237], v[20:21]
	v_pk_mul_f32 v[18:19], v[238:239], v[22:23]
	v_cvt_pk_bf16_f32 v16, v16, v17
	v_cvt_pk_bf16_f32 v17, v18, v19
	global_store_dwordx2 v[4:5], v[16:17], off offset:1024
	v_pk_mul_f32 v[20:21], v[28:29], v[36:37] op_sel_hi:[1,0]
	v_pk_mul_f32 v[22:23], v[30:31], v[36:37] op_sel_hi:[1,0]
	v_pk_mul_f32 v[16:17], v[240:241], v[20:21]
	v_pk_mul_f32 v[18:19], v[242:243], v[22:23]
	v_cvt_pk_bf16_f32 v16, v16, v17
	v_cvt_pk_bf16_f32 v17, v18, v19
	global_store_dwordx2 v[4:5], v[16:17], off offset:1536
	v_lshl_add_u64 v[4:5], v[4:5], 0, s[0:1]
	s_cmp_lg_u32 s98, 0
	s_cbranch_scc1 .LBB0_218
